# LS1 on MM1+PL1+PW1: phase 0 waves 4-7 stream rows [0,28672), waves 0-3 convert rows [28672,32768) after their small work; phase 1 as PW1 (rows >= 32768)
# baseline (speedup 1.0000x reference)
; __device__ void p0_xconv(const Args& a) {
;     f16* XH = (f16*)(a.ws + WS_XH); float* SS = (float*)(a.ws + WS_SS);
;     int tid_ = threadIdx.x; asm volatile("" : "+v"(tid_));
;     const int lane = tid_ & 63, wv = tid_ >> 6;
;     const int nwv = (int)gridDim.x * 8;
;     for (int row0 = (int)blockIdx.x * 8 + wv; row0 < MROWS; row0 += 4 * nwv) {
;         f32x4 v[4][4];
; #pragma unroll
;         for (int r = 0; r < 4; ++r) {
;             const int row = row0 + r * nwv;
;             if (row < MROWS) {
;                 const float* src = (row < ROWS_PROMPT) ? a.x_prompt + (size_t)row * DM : a.x_sample + (size_t)(row - ROWS_PROMPT) * DM;
; #pragma unroll
;                 for (int i = 0; i < 4; ++i) v[r][i] = __builtin_nontemporal_load((const f32x4*)(src + i * 256 + lane * 4));
;             }
;         }
; #pragma unroll
;         for (int r = 0; r < 4; ++r) {
;             const int row = row0 + r * nwv;
;             if (row < MROWS) {
;                 float ss = 0.f;
; #pragma unroll
;                 for (int i = 0; i < 4; ++i) {
;                     const f32x4 x = v[r][i];
;                     ss += (x[0] * x[0] + x[1] * x[1]) + (x[2] * x[2] + x[3] * x[3]);
;                     f16x4 h; h[0] = (f16)x[0]; h[1] = (f16)x[1]; h[2] = (f16)x[2]; h[3] = (f16)x[3];
;                     *(f16x4*)(XH + (size_t)row * DM + i * 256 + lane * 4) = h;
;                 }
; #pragma unroll
;                 for (int o = 1; o < 64; o <<= 1) ss += __shfl_xor(ss, o);
;                 if (lane < 16) SS[(size_t)row * 16 + lane] = (lane == 0) ? ss : 0.f;
;             }
.Lws_done:
	v_add_u32_e32 v0, 0xffffff00, v0
	v_and_b32_e32 v136, 63, v0
	v_lshrrev_b32_e32 v137, 6, v0
	s_nop 0
	v_readfirstlane_b32 s3, v137
	s_nop 3
	s_lshl_b32 s4, s2, 2
	s_add_i32 s3, s3, s4
	s_mov_b64 s[12:13], 1
	v_xor_b32_e32 v130, 1, v136
	v_lshlrev_b32_e32 v130, 2, v130
	v_xor_b32_e32 v131, 2, v136
	v_lshlrev_b32_e32 v131, 2, v131
	v_xor_b32_e32 v132, 4, v136
	v_lshlrev_b32_e32 v132, 2, v132
	v_xor_b32_e32 v133, 8, v136
	v_lshlrev_b32_e32 v133, 2, v133
	v_xor_b32_e32 v134, 16, v136
	v_lshlrev_b32_e32 v134, 2, v134
	v_xor_b32_e32 v135, 32, v136
	v_lshlrev_b32_e32 v135, 2, v135
	v_lshlrev_b32_e32 v140, 4, v136
	v_lshlrev_b32_e32 v144, 3, v136
	v_lshlrev_b32_e32 v186, 2, v136
	v_lshlrev_b32_e32 v141, 4, v136
	v_add_u32_e32 v141, 0x400000, v141
	v_lshlrev_b32_e32 v145, 3, v136
	v_add_u32_e32 v145, 0x200000, v145
	v_lshlrev_b32_e32 v187, 2, v136
	v_add_u32_e32 v187, 0x10000, v187
	v_lshlrev_b32_e32 v142, 4, v136
	v_add_u32_e32 v142, 0x800000, v142
	v_lshlrev_b32_e32 v146, 3, v136
	v_add_u32_e32 v146, 0x400000, v146
	v_lshlrev_b32_e32 v188, 2, v136
	v_add_u32_e32 v188, 0x20000, v188
	v_lshlrev_b32_e32 v143, 4, v136
	v_add_u32_e32 v143, 0xc00000, v143
	v_lshlrev_b32_e32 v147, 3, v136
	v_add_u32_e32 v147, 0x600000, v147
	v_lshlrev_b32_e32 v189, 2, v136
	v_add_u32_e32 v189, 0x30000, v189
	s_add_i32 s6, s3, 0x3000
	s_lshl_b32 s6, s6, 12
	s_add_u32 s4, s18, s6
	s_addc_u32 s5, s19, 0
	global_load_dwordx4 v[2:5], v140, s[4:5] nt
	global_load_dwordx4 v[6:9], v140, s[4:5] offset:1024 nt
	global_load_dwordx4 v[10:13], v140, s[4:5] offset:2048 nt
	global_load_dwordx4 v[14:17], v140, s[4:5] offset:3072 nt
	global_load_dwordx4 v[18:21], v141, s[4:5] nt
	global_load_dwordx4 v[22:25], v141, s[4:5] offset:1024 nt
	global_load_dwordx4 v[26:29], v141, s[4:5] offset:2048 nt
	global_load_dwordx4 v[30:33], v141, s[4:5] offset:3072 nt
	global_load_dwordx4 v[34:37], v142, s[4:5] nt
	global_load_dwordx4 v[38:41], v142, s[4:5] offset:1024 nt
	global_load_dwordx4 v[42:45], v142, s[4:5] offset:2048 nt
	global_load_dwordx4 v[46:49], v142, s[4:5] offset:3072 nt
	global_load_dwordx4 v[50:53], v143, s[4:5] nt
	global_load_dwordx4 v[54:57], v143, s[4:5] offset:1024 nt
	global_load_dwordx4 v[58:61], v143, s[4:5] offset:2048 nt
	global_load_dwordx4 v[62:65], v143, s[4:5] offset:3072 nt
	s_waitcnt vmcnt(0)
	s_add_i32 s6, s3, 0x7000
	s_lshl_b32 s7, s6, 11
	s_add_u32 s10, s40, s7
	s_addc_u32 s11, s41, 0
	s_lshl_b32 s7, s6, 6
	s_add_u32 s6, s40, s7
	s_addc_u32 s7, s41, 0
	s_add_u32 s6, s6, 0x1f800000
	s_addc_u32 s7, s7, 0
	v_mul_f32_e32 v150, v3, v3
	v_mul_f32_e32 v151, v5, v5
	v_fmac_f32_e32 v150, v2, v2
	v_fmac_f32_e32 v151, v4, v4
	v_add_f32_e32 v160, v150, v151
	v_cvt_pk_f16_f32 v170, v2, v3
	v_cvt_pk_f16_f32 v171, v4, v5
	v_mul_f32_e32 v150, v7, v7
	v_mul_f32_e32 v151, v9, v9
	v_fmac_f32_e32 v150, v6, v6
	v_fmac_f32_e32 v151, v8, v8
	v_add_f32_e32 v152, v150, v151
	v_add_f32_e32 v160, v160, v152
	v_cvt_pk_f16_f32 v172, v6, v7
	v_cvt_pk_f16_f32 v173, v8, v9
	v_mul_f32_e32 v150, v11, v11
	v_mul_f32_e32 v151, v13, v13
	v_fmac_f32_e32 v150, v10, v10
	v_fmac_f32_e32 v151, v12, v12
	v_add_f32_e32 v152, v150, v151
	v_add_f32_e32 v160, v160, v152
	v_cvt_pk_f16_f32 v174, v10, v11
	v_cvt_pk_f16_f32 v175, v12, v13
	v_mul_f32_e32 v150, v15, v15
	v_mul_f32_e32 v151, v17, v17
	v_fmac_f32_e32 v150, v14, v14
	v_fmac_f32_e32 v151, v16, v16
	v_add_f32_e32 v152, v150, v151
	v_add_f32_e32 v160, v160, v152
	v_cvt_pk_f16_f32 v176, v14, v15
	v_cvt_pk_f16_f32 v177, v16, v17
	global_store_dwordx2 v144, v[170:171], s[10:11]
	global_store_dwordx2 v144, v[172:173], s[10:11] offset:512
	global_store_dwordx2 v144, v[174:175], s[10:11] offset:1024
	global_store_dwordx2 v144, v[176:177], s[10:11] offset:1536
	v_mul_f32_e32 v150, v19, v19
	v_mul_f32_e32 v151, v21, v21
	v_fmac_f32_e32 v150, v18, v18
	v_fmac_f32_e32 v151, v20, v20
	v_add_f32_e32 v161, v150, v151
	v_cvt_pk_f16_f32 v178, v18, v19
	v_cvt_pk_f16_f32 v179, v20, v21
	v_mul_f32_e32 v150, v23, v23
	v_mul_f32_e32 v151, v25, v25
	v_fmac_f32_e32 v150, v22, v22
	v_fmac_f32_e32 v151, v24, v24
	v_add_f32_e32 v152, v150, v151
	v_add_f32_e32 v161, v161, v152
	v_cvt_pk_f16_f32 v180, v22, v23
	v_cvt_pk_f16_f32 v181, v24, v25
	v_mul_f32_e32 v150, v27, v27
	v_mul_f32_e32 v151, v29, v29
	v_fmac_f32_e32 v150, v26, v26
	v_fmac_f32_e32 v151, v28, v28
	v_add_f32_e32 v152, v150, v151
	v_add_f32_e32 v161, v161, v152
	v_cvt_pk_f16_f32 v182, v26, v27
	v_cvt_pk_f16_f32 v183, v28, v29
	v_mul_f32_e32 v150, v31, v31
	v_mul_f32_e32 v151, v33, v33
	v_fmac_f32_e32 v150, v30, v30
	v_fmac_f32_e32 v151, v32, v32
	v_add_f32_e32 v152, v150, v151
	v_add_f32_e32 v161, v161, v152
	v_cvt_pk_f16_f32 v184, v30, v31
	v_cvt_pk_f16_f32 v185, v32, v33
	global_store_dwordx2 v145, v[178:179], s[10:11]
; __device__ void p0_xconv(const Args& a) {
;     ...
; #pragma unroll
;         for (int r = 0; r < 4; ++r) {
;             const int row = row0 + r * nwv;
;             if (row < MROWS) {
;                 float ss = 0.f;
; #pragma unroll
;                 for (int i = 0; i < 4; ++i) {
;                     const f32x4 x = v[r][i];
;                     ss += (x[0] * x[0] + x[1] * x[1]) + (x[2] * x[2] + x[3] * x[3]);
;                     f16x4 h; h[0] = (f16)x[0]; h[1] = (f16)x[1]; h[2] = (f16)x[2]; h[3] = (f16)x[3];
;                     *(f16x4*)(XH + (size_t)row * DM + i * 256 + lane * 4) = h;
;                 }
; #pragma unroll
;                 for (int o = 1; o < 64; o <<= 1) ss += __shfl_xor(ss, o);
;                 if (lane < 16) SS[(size_t)row * 16 + lane] = (lane == 0) ? ss : 0.f;
;             }
	global_store_dwordx2 v145, v[180:181], s[10:11] offset:512
	global_store_dwordx2 v145, v[182:183], s[10:11] offset:1024
	global_store_dwordx2 v145, v[184:185], s[10:11] offset:1536
	v_mul_f32_e32 v150, v35, v35
	v_mul_f32_e32 v151, v37, v37
	v_fmac_f32_e32 v150, v34, v34
	v_fmac_f32_e32 v151, v36, v36
	v_add_f32_e32 v162, v150, v151
	v_cvt_pk_f16_f32 v170, v34, v35
	v_cvt_pk_f16_f32 v171, v36, v37
	v_mul_f32_e32 v150, v39, v39
	v_mul_f32_e32 v151, v41, v41
	v_fmac_f32_e32 v150, v38, v38
	v_fmac_f32_e32 v151, v40, v40
	v_add_f32_e32 v152, v150, v151
	v_add_f32_e32 v162, v162, v152
	v_cvt_pk_f16_f32 v172, v38, v39
	v_cvt_pk_f16_f32 v173, v40, v41
	v_mul_f32_e32 v150, v43, v43
	v_mul_f32_e32 v151, v45, v45
	v_fmac_f32_e32 v150, v42, v42
	v_fmac_f32_e32 v151, v44, v44
	v_add_f32_e32 v152, v150, v151
	v_add_f32_e32 v162, v162, v152
	v_cvt_pk_f16_f32 v174, v42, v43
	v_cvt_pk_f16_f32 v175, v44, v45
	v_mul_f32_e32 v150, v47, v47
	v_mul_f32_e32 v151, v49, v49
	v_fmac_f32_e32 v150, v46, v46
	v_fmac_f32_e32 v151, v48, v48
	v_add_f32_e32 v152, v150, v151
	v_add_f32_e32 v162, v162, v152
	v_cvt_pk_f16_f32 v176, v46, v47
	v_cvt_pk_f16_f32 v177, v48, v49
	global_store_dwordx2 v146, v[170:171], s[10:11]
	global_store_dwordx2 v146, v[172:173], s[10:11] offset:512
	global_store_dwordx2 v146, v[174:175], s[10:11] offset:1024
	global_store_dwordx2 v146, v[176:177], s[10:11] offset:1536
	v_mul_f32_e32 v150, v51, v51
	v_mul_f32_e32 v151, v53, v53
	v_fmac_f32_e32 v150, v50, v50
	v_fmac_f32_e32 v151, v52, v52
	v_add_f32_e32 v163, v150, v151
	v_cvt_pk_f16_f32 v178, v50, v51
	v_cvt_pk_f16_f32 v179, v52, v53
	v_mul_f32_e32 v150, v55, v55
	v_mul_f32_e32 v151, v57, v57
	v_fmac_f32_e32 v150, v54, v54
	v_fmac_f32_e32 v151, v56, v56
	v_add_f32_e32 v152, v150, v151
	v_add_f32_e32 v163, v163, v152
	v_cvt_pk_f16_f32 v180, v54, v55
	v_cvt_pk_f16_f32 v181, v56, v57
	v_mul_f32_e32 v150, v59, v59
	v_mul_f32_e32 v151, v61, v61
	v_fmac_f32_e32 v150, v58, v58
	v_fmac_f32_e32 v151, v60, v60
	v_add_f32_e32 v152, v150, v151
	v_add_f32_e32 v163, v163, v152
	v_cvt_pk_f16_f32 v182, v58, v59
	v_cvt_pk_f16_f32 v183, v60, v61
	v_mul_f32_e32 v150, v63, v63
	v_mul_f32_e32 v151, v65, v65
	v_fmac_f32_e32 v150, v62, v62
	v_fmac_f32_e32 v151, v64, v64
	v_add_f32_e32 v152, v150, v151
	v_add_f32_e32 v163, v163, v152
	v_cvt_pk_f16_f32 v184, v62, v63
	v_cvt_pk_f16_f32 v185, v64, v65
	global_store_dwordx2 v147, v[178:179], s[10:11]
	global_store_dwordx2 v147, v[180:181], s[10:11] offset:512
	global_store_dwordx2 v147, v[182:183], s[10:11] offset:1024
	global_store_dwordx2 v147, v[184:185], s[10:11] offset:1536
	ds_bpermute_b32 v164, v130, v160
	ds_bpermute_b32 v165, v130, v161
	ds_bpermute_b32 v166, v130, v162
	ds_bpermute_b32 v167, v130, v163
	s_waitcnt lgkmcnt(0)
	v_add_f32_e32 v160, v160, v164
	v_add_f32_e32 v161, v161, v165
	v_add_f32_e32 v162, v162, v166
	v_add_f32_e32 v163, v163, v167
	ds_bpermute_b32 v164, v131, v160
	ds_bpermute_b32 v165, v131, v161
	ds_bpermute_b32 v166, v131, v162
	ds_bpermute_b32 v167, v131, v163
	s_waitcnt lgkmcnt(0)
	v_add_f32_e32 v160, v160, v164
	v_add_f32_e32 v161, v161, v165
	v_add_f32_e32 v162, v162, v166
	v_add_f32_e32 v163, v163, v167
	ds_bpermute_b32 v164, v132, v160
	ds_bpermute_b32 v165, v132, v161
	ds_bpermute_b32 v166, v132, v162
	ds_bpermute_b32 v167, v132, v163
	s_waitcnt lgkmcnt(0)
	v_add_f32_e32 v160, v160, v164
	v_add_f32_e32 v161, v161, v165
	v_add_f32_e32 v162, v162, v166
	v_add_f32_e32 v163, v163, v167
	ds_bpermute_b32 v164, v133, v160
	ds_bpermute_b32 v165, v133, v161
	ds_bpermute_b32 v166, v133, v162
	ds_bpermute_b32 v167, v133, v163
	s_waitcnt lgkmcnt(0)
	v_add_f32_e32 v160, v160, v164
	v_add_f32_e32 v161, v161, v165
	v_add_f32_e32 v162, v162, v166
	v_add_f32_e32 v163, v163, v167
	ds_bpermute_b32 v164, v134, v160
	ds_bpermute_b32 v165, v134, v161
	ds_bpermute_b32 v166, v134, v162
	ds_bpermute_b32 v167, v134, v163
	s_waitcnt lgkmcnt(0)
	v_add_f32_e32 v160, v160, v164
	v_add_f32_e32 v161, v161, v165
	v_add_f32_e32 v162, v162, v166
	v_add_f32_e32 v163, v163, v167
	ds_bpermute_b32 v164, v135, v160
	ds_bpermute_b32 v165, v135, v161
	ds_bpermute_b32 v166, v135, v162
	ds_bpermute_b32 v167, v135, v163
	s_waitcnt lgkmcnt(0)
	v_add_f32_e32 v160, v160, v164
	v_add_f32_e32 v161, v161, v165
	v_add_f32_e32 v162, v162, v166
	v_add_f32_e32 v163, v163, v167
	v_cndmask_b32_e64 v164, 0, v160, s[12:13]
	v_cndmask_b32_e64 v165, 0, v161, s[12:13]
	v_cndmask_b32_e64 v166, 0, v162, s[12:13]
	v_cndmask_b32_e64 v167, 0, v163, s[12:13]
	s_mov_b64 exec, 0xffff
	global_store_dword v186, v164, s[6:7]
	global_store_dword v187, v165, s[6:7]
	global_store_dword v188, v166, s[6:7]
	global_store_dword v189, v167, s[6:7]
	s_mov_b64 exec, -1
	s_branch .LBB0_37
